# NA attention running-max xor-32 shuffle: ds_bpermute replaced by v_permlane32_swap (no LDS round trip)
# baseline (speedup 1.0000x reference)
; #define LAS __attribute__((address_space(3)))
; __device__ __forceinline__ void na_attn(const Ctx& c, const bf16_t* qkv, const float* rpb, bf16_t* o) {
;     ...
;             __syncthreads();
; #pragma unroll
;             for (int e = 0; e < 2; ++e) {
;                 const int hl = 2 * c.wave + e; const LAS float* bp = rp + (hl * 15 + dr) * 31;
;                 f32x16 S0, S1;
; #pragma unroll
;                 for (int i = 0; i < 16; ++i) { S0[i] = 0.f; S1[i] = 0.f; }
; #pragma unroll
;                 for (int s = 0; s < 2; ++s) {
;                     const bf16x8 A0 = *(const LAS bf16x8*)(KV + ql * 1024 + hl * 64 + (16 * s + 8 * h) * 2), A1 = *(const LAS bf16x8*)(KV + (8 + ql) * 1024 + hl * 64 + (16 * s + 8 * h) * 2);
;                     S0 = __builtin_amdgcn_mfma_f32_32x32x16_bf16(A0, Qf[e][s], S0, 0, 0, 0); S1 = __builtin_amdgcn_mfma_f32_32x32x16_bf16(A1, Qf[e][s], S1, 0, 0, 0); }
;                 const float sc = 0.17677669529663687f * 1.44269504089f;
;                 float mloc = -1e30f;
; #pragma unroll
;                 for (int i = 0; i < 16; ++i) { const int ci = (i & 3) + 8 * (i >> 2) + 4 * h;
;                     { const int kcol = kcb0 + ci; const bool ok = kcol >= qsl && kcol < qsl + 16; const int dc = ok ? kcol - qc + 15 : 0; const float v = ok ? S0[i] * sc + bp[dc] : -1e30f; S0[i] = v; mloc = fmaxf(mloc, v); }
;                     if (i >= 12) {
;                       const int kcol = kcb0 + 8 + ci; const bool ok = kcol >= qsl && kcol < qsl + 16; const int dc = ok ? kcol - qc + 15 : 0; const float v = ok ? S1[i] * sc + bp[dc] : -1e30f; S1[i] = v; mloc = fmaxf(mloc, v); } }
;                 mloc = fmaxf(mloc, __shfl_xor(mloc, 32));
;                 const float mn = fmaxf(mrun[e], mloc), corr = __builtin_amdgcn_exp2f(mrun[e] - mn); mrun[e] = mn;
;                 float lsum = 0.f;
; #pragma unroll
;                 for (int i = 0; i < 16; ++i) { O[e][i] *= corr; S0[i] = __builtin_amdgcn_exp2f(S0[i] - mn); lsum += S0[i];
;                     if (i >= 12) { S1[i] = __builtin_amdgcn_exp2f(S1[i] - mn); lsum += S1[i]; } else S1[i] = 0.f; }
;                 lrun[e] = lrun[e] * corr + lsum;
;                 const LAS bf16_t* vb = VT + hl * VH + ql * VP + 4 * h;
; #pragma unroll
;                 for (int kt = 0; kt < 2; ++kt)
; #pragma unroll
;                     for (int s = kt; s < 2; ++s) {
;                         u32x4 pw;
.LBB1_477:
	s_waitcnt lgkmcnt(0)
	s_barrier
	ds_read_b128 v[38:41], v208
	ds_read_b128 v[226:229], v208 offset:32
	s_waitcnt vmcnt(13) lgkmcnt(1)
	v_mfma_f32_32x32x16_bf16 v[54:69], v[38:41], v[0:3], 0
	ds_read_b128 v[38:41], v208 offset:8192
	ds_read_b128 v[230:233], v208 offset:8224
	s_waitcnt lgkmcnt(1)
	v_mfma_f32_32x32x16_bf16 v[38:53], v[38:41], v[0:3], 0
	s_waitcnt vmcnt(12)
	v_mfma_f32_32x32x16_bf16 v[54:69], v[226:229], v[70:73], v[54:69]
	v_mov_b32_e32 v228, 0xf149f2ca
	v_add_u32_e32 v226, s65, v217
	v_mov_b32_e32 v229, 0xf149f2ca
	s_waitcnt lgkmcnt(0)
	v_mfma_f32_32x32x16_bf16 v[38:53], v[230:233], v[70:73], v[38:53]
	v_add_u32_e32 v227, 0x174a0, v226
	ds_read_b32 v230, v227 offset:0
	ds_read_b32 v231, v227 offset:4
	ds_read_b32 v232, v227 offset:8
	ds_read_b32 v233, v227 offset:12
	ds_read_b32 v234, v227 offset:32
	ds_read_b32 v235, v227 offset:36
	ds_read_b32 v236, v227 offset:40
	ds_read_b32 v237, v227 offset:44
	ds_read_b32 v238, v227 offset:64
	ds_read_b32 v239, v227 offset:68
	ds_read_b32 v240, v227 offset:72
	ds_read_b32 v241, v227 offset:76
	ds_read_b32 v242, v227 offset:96
	ds_read_b32 v243, v227 offset:128
	ds_read_b32 v244, v227 offset:100
	ds_read_b32 v245, v227 offset:132
	ds_read_b32 v246, v227 offset:104
	ds_read_b32 v247, v227 offset:136
	s_waitcnt lgkmcnt(0)
	v_fmac_f32_e32 v230, 0x3e8293ee, v54
	v_cndmask_b32_e64 v229, v229, v230, s[30:31]
	v_fmac_f32_e32 v231, 0x3e8293ee, v55
	v_cndmask_b32_e64 v228, v228, v231, s[28:29]
	s_nop 5
	v_mov_b32_e32 v38, 0xf149f2ca
	v_mov_b32_e32 v39, 0xf149f2ca
	v_fmac_f32_e32 v232, 0x3e8293ee, v56
	v_cndmask_b32_e64 v39, v39, v232, s[36:37]
	v_fmac_f32_e32 v233, 0x3e8293ee, v57
	v_cndmask_b32_e64 v38, v38, v233, s[92:93]
	v_mov_b32_e32 v40, 0xf149f2ca
	v_mov_b32_e32 v41, 0xf149f2ca
	v_fmac_f32_e32 v234, 0x3e8293ee, v58
	v_cndmask_b32_e64 v41, v41, v234, s[6:7]
	v_fmac_f32_e32 v235, 0x3e8293ee, v59
	v_cndmask_b32_e64 v40, v40, v235, s[70:71]
	v_mov_b32_e32 v42, 0xf149f2ca
	v_mov_b32_e32 v43, 0xf149f2ca
	v_fmac_f32_e32 v236, 0x3e8293ee, v60
	v_cndmask_b32_e64 v43, v43, v236, s[38:39]
	v_fmac_f32_e32 v237, 0x3e8293ee, v61
	v_cndmask_b32_e64 v42, v42, v237, s[40:41]
	v_mov_b32_e32 v44, 0xf149f2ca
	v_mov_b32_e32 v46, 0xf149f2ca
	v_fmac_f32_e32 v238, 0x3e8293ee, v62
	v_cndmask_b32_e64 v46, v46, v238, s[42:43]
	v_fmac_f32_e32 v239, 0x3e8293ee, v63
	v_cndmask_b32_e64 v44, v44, v239, s[44:45]
	v_mov_b32_e32 v47, 0xf149f2ca
	v_mov_b32_e32 v48, 0xf149f2ca
	v_fmac_f32_e32 v240, 0x3e8293ee, v64
	v_cndmask_b32_e64 v48, v48, v240, s[46:47]
	v_fmac_f32_e32 v241, 0x3e8293ee, v65
	v_cndmask_b32_e64 v47, v47, v241, s[48:49]
	v_mov_b32_e32 v54, 0xf149f2ca
	v_mov_b32_e32 v55, 0xf149f2ca
	v_fmac_f32_e32 v242, 0x3e8293ee, v66
	v_cndmask_b32_e64 v55, v55, v242, s[50:51]
	v_fmac_f32_e32 v243, 0x3e8293ee, v50
	v_cndmask_b32_e64 v54, v54, v243, s[52:53]
	v_mov_b32_e32 v45, 0xf149f2ca
	v_mov_b32_e32 v56, 0xf149f2ca
	v_fmac_f32_e32 v244, 0x3e8293ee, v67
	v_cndmask_b32_e64 v56, v56, v244, s[54:55]
	v_fmac_f32_e32 v245, 0x3e8293ee, v51
	v_cndmask_b32_e64 v45, v45, v245, s[56:57]
	v_mov_b32_e32 v49, 0xf149f2ca
	v_mov_b32_e32 v51, 0xf149f2ca
	v_fmac_f32_e32 v246, 0x3e8293ee, v68
	v_cndmask_b32_e64 v51, v51, v246, s[58:59]
	v_fmac_f32_e32 v247, 0x3e8293ee, v52
	v_cndmask_b32_e64 v49, v49, v247, s[60:61]
	v_mov_b32_e32 v50, 0xf149f2ca
	v_mov_b32_e32 v52, 0xf149f2ca
	v_add_u32_e32 v227, 0x174a0, v226
	ds_read_b32 v230, v227 offset:108
	ds_read_b32 v231, v227 offset:140
	s_waitcnt lgkmcnt(0)
	v_fmac_f32_e32 v230, 0x3e8293ee, v69
	v_cndmask_b32_e64 v52, v52, v230, s[62:63]
	v_fmac_f32_e32 v231, 0x3e8293ee, v53
	v_cndmask_b32_e64 v50, v50, v231, s[0:1]
	v_mov_b32_e32 v227, 0xf149f2ca
	v_max3_f32 v53, v229, v227, v228
	v_max3_f32 v53, v53, v39, v38
	v_max3_f32 v53, v53, v41, v40
	v_max3_f32 v53, v53, v43, v42
	v_max3_f32 v53, v53, v46, v44
	v_max3_f32 v53, v53, v48, v47
	v_max3_f32 v53, v53, v55, v54
	v_max3_f32 v53, v53, v56, v45
	v_max3_f32 v53, v53, v51, v49
	v_max3_f32 v53, v53, v52, v50
	v_mov_b32_e32 v57, v53
	s_nop 1
	v_permlane32_swap_b32 v57, v53
	s_mul_i32 s66, s3, 0x1a20
	s_waitcnt lgkmcnt(0)
	v_max3_f32 v225, v4, v53, v57
	v_sub_f32_e32 v38, v38, v225
	v_exp_f32_e32 v231, v38
	v_sub_f32_e32 v38, v41, v225
	v_exp_f32_e32 v232, v38
	v_sub_f32_e32 v38, v40, v225
	v_exp_f32_e32 v233, v38
	v_sub_f32_e32 v38, v43, v225
	v_exp_f32_e32 v234, v38
	v_sub_f32_e32 v38, v42, v225
	v_exp_f32_e32 v235, v38
	v_sub_f32_e32 v38, v46, v225
	v_exp_f32_e32 v236, v38
	v_sub_f32_e32 v38, v44, v225
	v_exp_f32_e32 v237, v38
	v_sub_f32_e32 v38, v48, v225
	v_exp_f32_e32 v238, v38
	v_sub_f32_e32 v38, v47, v225
	v_exp_f32_e32 v239, v38
	v_sub_f32_e32 v38, v55, v225
	v_exp_f32_e32 v240, v38
	v_sub_f32_e32 v38, v56, v225
	v_add_u32_e32 v43, s66, v130
	v_sub_f32_e32 v53, v229, v225
	v_sub_f32_e32 v57, v228, v225
	v_sub_f32_e32 v39, v39, v225
	v_exp_f32_e32 v241, v38
	v_sub_f32_e32 v38, v51, v225
	v_add_u32_e32 v43, 0xa000, v43
	v_exp_f32_e32 v228, v53
	v_exp_f32_e32 v229, v57
	v_exp_f32_e32 v230, v39
	v_sub_f32_e32 v42, v54, v225
	v_exp_f32_e32 v242, v38
	v_cvt_pk_bf16_f32 v38, v228, v229
	v_cvt_pk_bf16_f32 v39, v230, v231
	v_cvt_pk_bf16_f32 v40, v232, v233
	v_cvt_pk_bf16_f32 v41, v234, v235
	ds_read2_b64 v[54:57], v43 offset1:2
	v_sub_f32_e32 v4, v4, v225
	v_exp_f32_e32 v4, v4
	v_sub_f32_e32 v44, v52, v225
	v_exp_f32_e32 v243, v44
	v_cvt_pk_bf16_f32 v58, v236, v237
	v_pk_mul_f32 v[22:23], v[22:23], v[4:5] op_sel_hi:[1,0]
	v_pk_mul_f32 v[24:25], v[24:25], v[4:5] op_sel_hi:[1,0]
	v_pk_mul_f32 v[26:27], v[26:27], v[4:5] op_sel_hi:[1,0]
	v_pk_mul_f32 v[28:29], v[28:29], v[4:5] op_sel_hi:[1,0]
	v_pk_mul_f32 v[30:31], v[30:31], v[4:5] op_sel_hi:[1,0]
	v_pk_mul_f32 v[32:33], v[32:33], v[4:5] op_sel_hi:[1,0]
	v_pk_mul_f32 v[34:35], v[34:35], v[4:5] op_sel_hi:[1,0]
	v_pk_mul_f32 v[36:37], v[36:37], v[4:5] op_sel_hi:[1,0]
	v_cvt_pk_bf16_f32 v59, v238, v239
	v_cvt_pk_bf16_f32 v60, v240, v241
	v_cvt_pk_bf16_f32 v61, v242, v243
	ds_read2_b64 v[62:65], v43 offset0:4 offset1:6
	v_exp_f32_e32 v244, v42
	s_waitcnt lgkmcnt(1)
; #define LAS __attribute__((address_space(3)))
; __device__ __forceinline__ void na_attn(const Ctx& c, const bf16_t* qkv, const float* rpb, bf16_t* o) {
;     ...
; #pragma unroll
;                 for (int s = 0; s < 2; ++s) {
;                     const bf16x8 A0 = *(const LAS bf16x8*)(KV + ql * 1024 + hl * 64 + (16 * s + 8 * h) * 2), A1 = *(const LAS bf16x8*)(KV + (8 + ql) * 1024 + hl * 64 + (16 * s + 8 * h) * 2);
;                     S0 = __builtin_amdgcn_mfma_f32_32x32x16_bf16(A0, Qf[e][s], S0, 0, 0, 0); S1 = __builtin_amdgcn_mfma_f32_32x32x16_bf16(A1, Qf[e][s], S1, 0, 0, 0); }
;                 const float sc = 0.17677669529663687f * 1.44269504089f;
;                 float mloc = -1e30f;
; #pragma unroll
;                 for (int i = 0; i < 16; ++i) { const int ci = (i & 3) + 8 * (i >> 2) + 4 * h;
;                     { const int kcol = kcb0 + ci; const bool ok = kcol >= qsl && kcol < qsl + 16; const int dc = ok ? kcol - qc + 15 : 0; const float v = ok ? S0[i] * sc + bp[dc] : -1e30f; S0[i] = v; mloc = fmaxf(mloc, v); }
;                     if (i >= 12) {
;                       const int kcol = kcb0 + 8 + ci; const bool ok = kcol >= qsl && kcol < qsl + 16; const int dc = ok ? kcol - qc + 15 : 0; const float v = ok ? S1[i] * sc + bp[dc] : -1e30f; S1[i] = v; mloc = fmaxf(mloc, v); } }
;                 mloc = fmaxf(mloc, __shfl_xor(mloc, 32));
;                 const float mn = fmaxf(mrun[e], mloc), corr = __builtin_amdgcn_exp2f(mrun[e] - mn); mrun[e] = mn;
;                 float lsum = 0.f;
; #pragma unroll
;                 for (int i = 0; i < 16; ++i) { O[e][i] *= corr; S0[i] = __builtin_amdgcn_exp2f(S0[i] - mn); lsum += S0[i];
;                     if (i >= 12) { S1[i] = __builtin_amdgcn_exp2f(S1[i] - mn); lsum += S1[i]; } else S1[i] = 0.f; }
;                 lrun[e] = lrun[e] * corr + lsum;
;                 const LAS bf16_t* vb = VT + hl * VH + ql * VP + 4 * h;
; #pragma unroll
;                 for (int kt = 0; kt < 2; ++kt)
; #pragma unroll
;                     for (int s = kt; s < 2; ++s) {
;                         u32x4 pw;
;                         if (kt == 0) { pw.x = cvt_pk_bf16(S0[8 * s], S0[8 * s + 1]); pw.y = cvt_pk_bf16(S0[8 * s + 2], S0[8 * s + 3]); pw.z = cvt_pk_bf16(S0[8 * s + 4], S0[8 * s + 5]); pw.w = cvt_pk_bf16(S0[8 * s + 6], S0[8 * s + 7]); }
	v_mfma_f32_32x32x16_bf16 v[22:37], v[54:57], v[38:41], v[22:37]
	v_sub_f32_e32 v38, v45, v225
	v_exp_f32_e32 v245, v38
	v_sub_f32_e32 v38, v49, v225
	v_exp_f32_e32 v246, v38
	v_sub_f32_e32 v38, v50, v225
	v_exp_f32_e32 v247, v38
	v_cvt_pk_bf16_f32 v38, v5, v5
	v_cvt_pk_bf16_f32 v39, v5, v5
	v_cvt_pk_bf16_f32 v40, v244, v245
	v_cvt_pk_bf16_f32 v41, v246, v247
	ds_read2_b64 v[42:45], v43 offset0:6 offset1:8
	s_waitcnt lgkmcnt(1)
	v_mfma_f32_32x32x16_bf16 v[22:37], v[62:65], v[58:61], v[22:37]
	ds_read_b128 v[194:197], v209 offset:32
	s_waitcnt lgkmcnt(1)
	v_mfma_f32_32x32x16_bf16 v[22:37], v[42:45], v[38:41], v[22:37]
	ds_read_b128 v[38:41], v209
	s_waitcnt vmcnt(11) lgkmcnt(0)
	v_mfma_f32_32x32x16_bf16 v[54:69], v[38:41], v[74:77], 0
	ds_read_b128 v[38:41], v209 offset:8192
	s_waitcnt vmcnt(10)
	v_mfma_f32_32x32x16_bf16 v[54:69], v[194:197], v[78:81], v[54:69]
	ds_read_b128 v[194:197], v209 offset:8224
	s_waitcnt lgkmcnt(1)
	v_mfma_f32_32x32x16_bf16 v[38:53], v[38:41], v[74:77], 0
	s_waitcnt lgkmcnt(0)
	v_mfma_f32_32x32x16_bf16 v[38:53], v[194:197], v[78:81], v[38:53]
	s_nop 11
	v_mov_b32_e32 v43, 0xf149f2ca
	v_add_u32_e32 v38, 0x17be4, v226
	ds_read_b32 v194, v38 offset:0
	ds_read_b32 v195, v38 offset:4
	ds_read_b32 v196, v38 offset:8
	ds_read_b32 v197, v38 offset:12
	ds_read_b32 v192, v38 offset:32
	ds_read_b32 v193, v38 offset:36
	ds_read_b32 v198, v38 offset:40
	ds_read_b32 v173, v38 offset:44
	ds_read_b32 v248, v38 offset:64
	ds_read_b32 v249, v38 offset:68
	s_waitcnt lgkmcnt(0)
	v_fmac_f32_e32 v194, 0x3e8293ee, v54
	v_cndmask_b32_e64 v43, v43, v194, s[30:31]
	v_fmac_f32_e32 v195, 0x3e8293ee, v55
	v_cndmask_b32_e64 v227, v227, v195, s[28:29]
	v_mov_b32_e32 v39, 0xf149f2ca
	v_mov_b32_e32 v44, 0xf149f2ca
	v_fmac_f32_e32 v196, 0x3e8293ee, v56
	v_cndmask_b32_e64 v44, v44, v196, s[36:37]
	v_fmac_f32_e32 v197, 0x3e8293ee, v57
	v_cndmask_b32_e64 v39, v39, v197, s[92:93]
	v_mov_b32_e32 v40, 0xf149f2ca
	v_mov_b32_e32 v46, 0xf149f2ca
	v_fmac_f32_e32 v192, 0x3e8293ee, v58
	v_cndmask_b32_e64 v46, v46, v192, s[6:7]
	v_fmac_f32_e32 v193, 0x3e8293ee, v59
	v_cndmask_b32_e64 v40, v40, v193, s[70:71]
	v_mov_b32_e32 v41, 0xf149f2ca
	v_mov_b32_e32 v47, 0xf149f2ca
	v_fmac_f32_e32 v198, 0x3e8293ee, v60
	v_cndmask_b32_e64 v47, v47, v198, s[38:39]
	v_fmac_f32_e32 v173, 0x3e8293ee, v61
	v_cndmask_b32_e64 v41, v41, v173, s[40:41]
	v_mov_b32_e32 v42, 0xf149f2ca
	v_mov_b32_e32 v48, 0xf149f2ca
	v_fmac_f32_e32 v248, 0x3e8293ee, v62
	v_cndmask_b32_e64 v48, v48, v248, s[42:43]
	v_fmac_f32_e32 v249, 0x3e8293ee, v63
	v_cndmask_b32_e64 v42, v42, v249, s[44:45]
	v_mov_b32_e32 v45, 0xf149f2ca
	v_mov_b32_e32 v54, 0xf149f2ca
	v_add_u32_e32 v38, 0x17be4, v226
	ds_read_b32 v194, v38 offset:72
	ds_read_b32 v195, v38 offset:76
	ds_read_b32 v196, v38 offset:96
	ds_read_b32 v197, v38 offset:128
	ds_read_b32 v192, v38 offset:100
	ds_read_b32 v193, v38 offset:132
	ds_read_b32 v198, v38 offset:104
	ds_read_b32 v173, v38 offset:136
	ds_read_b32 v248, v38 offset:108
	ds_read_b32 v249, v38 offset:140
	s_waitcnt lgkmcnt(0)
	v_fmac_f32_e32 v194, 0x3e8293ee, v64
	v_cndmask_b32_e64 v54, v54, v194, s[46:47]
	v_fmac_f32_e32 v195, 0x3e8293ee, v65
	v_cndmask_b32_e64 v45, v45, v195, s[48:49]
	v_mov_b32_e32 v49, 0xf149f2ca
	v_mov_b32_e32 v55, 0xf149f2ca
	v_fmac_f32_e32 v196, 0x3e8293ee, v66
	v_cndmask_b32_e64 v55, v55, v196, s[50:51]
	v_fmac_f32_e32 v197, 0x3e8293ee, v50
	v_cndmask_b32_e64 v49, v49, v197, s[52:53]
	v_mov_b32_e32 v50, 0xf149f2ca
	v_mov_b32_e32 v56, 0xf149f2ca
	v_fmac_f32_e32 v192, 0x3e8293ee, v67
	v_cndmask_b32_e64 v56, v56, v192, s[54:55]
	v_fmac_f32_e32 v193, 0x3e8293ee, v51
	v_cndmask_b32_e64 v50, v50, v193, s[56:57]
	v_mov_b32_e32 v51, 0xf149f2ca
	v_mov_b32_e32 v57, 0xf149f2ca
	v_fmac_f32_e32 v198, 0x3e8293ee, v68
	v_cndmask_b32_e64 v57, v57, v198, s[58:59]
	v_fmac_f32_e32 v173, 0x3e8293ee, v52
	v_cndmask_b32_e64 v51, v51, v173, s[60:61]
	v_mov_b32_e32 v52, 0xf149f2ca
	v_mov_b32_e32 v58, 0xf149f2ca
	v_fmac_f32_e32 v248, 0x3e8293ee, v69
	v_cndmask_b32_e64 v58, v58, v248, s[62:63]
	v_fmac_f32_e32 v249, 0x3e8293ee, v53
	v_cndmask_b32_e64 v52, v52, v249, s[0:1]
	s_mov_b32 s66, 0xf149f2ca
	v_max3_f32 v38, v43, s66, v227
	v_max3_f32 v38, v38, v44, v39
	v_max3_f32 v38, v38, v46, v40
	v_max3_f32 v38, v38, v47, v41
	v_max3_f32 v38, v38, v48, v42
	v_max3_f32 v38, v38, v54, v45
	v_max3_f32 v38, v38, v55, v49
	v_max3_f32 v38, v38, v56, v50
	v_max3_f32 v53, v38, v57, v51
	v_add_f32_e32 v38, 0, v228
	v_add_f32_e32 v38, v229, v38
	v_add_f32_e32 v38, v230, v38
	v_add_f32_e32 v38, v231, v38
	v_add_f32_e32 v38, v232, v38
	v_add_f32_e32 v38, v233, v38
	v_add_f32_e32 v38, v234, v38
	v_add_f32_e32 v38, v235, v38
	v_add_f32_e32 v38, v236, v38
	v_add_f32_e32 v38, v237, v38
	v_add_f32_e32 v38, v238, v38
	v_add_f32_e32 v38, v239, v38
	v_add_f32_e32 v38, v240, v38
	v_add_f32_e32 v38, v244, v38
	v_add_f32_e32 v38, v241, v38
	v_add_f32_e32 v38, v245, v38
	v_add_f32_e32 v38, v242, v38
	v_add_f32_e32 v38, v246, v38
	v_add_f32_e32 v38, v243, v38
	v_add_f32_e32 v38, v247, v38
	v_fmac_f32_e32 v38, v224, v4
	v_max3_f32 v4, v53, v58, v52
	v_mov_b32_e32 v53, v4
	s_nop 1
	v_permlane32_swap_b32 v53, v4
	s_addk_i32 s65, 0x7c
	v_add_u32_e32 v211, 0x60000, v211
	v_add_u32_e32 v212, 0x60000, v212
	v_add_u32_e32 v213, 0x60000, v213
	s_waitcnt lgkmcnt(0)
; #define LAS __attribute__((address_space(3)))
; __device__ __forceinline__ unsigned cvt_pk_bf16(float lo, float hi) { unsigned r; asm volatile("v_cvt_pk_bf16_f32 %0, %1, %2" : "=v"(r) : "v"(lo), "v"(hi)); return r; }
; __device__ __forceinline__ void na_attn(const Ctx& c, const bf16_t* qkv, const float* rpb, bf16_t* o) {
;     ...
;                 const float mn = fmaxf(mrun[e], mloc), corr = __builtin_amdgcn_exp2f(mrun[e] - mn); mrun[e] = mn;
;                 float lsum = 0.f;
; #pragma unroll
;                 for (int i = 0; i < 16; ++i) { O[e][i] *= corr; S0[i] = __builtin_amdgcn_exp2f(S0[i] - mn); lsum += S0[i];
;                     if (i >= 12) { S1[i] = __builtin_amdgcn_exp2f(S1[i] - mn); lsum += S1[i]; } else S1[i] = 0.f; }
;                 lrun[e] = lrun[e] * corr + lsum;
;                 const LAS bf16_t* vb = VT + hl * VH + ql * VP + 4 * h;
; #pragma unroll
;                 for (int kt = 0; kt < 2; ++kt)
; #pragma unroll
;                     for (int s = kt; s < 2; ++s) {
;                         u32x4 pw;
;                         if (kt == 0) { pw.x = cvt_pk_bf16(S0[8 * s], S0[8 * s + 1]); pw.y = cvt_pk_bf16(S0[8 * s + 2], S0[8 * s + 3]); pw.z = cvt_pk_bf16(S0[8 * s + 4], S0[8 * s + 5]); pw.w = cvt_pk_bf16(S0[8 * s + 6], S0[8 * s + 7]); }
;                         else { pw.x = cvt_pk_bf16(S1[8 * s], S1[8 * s + 1]); pw.y = cvt_pk_bf16(S1[8 * s + 2], S1[8 * s + 3]); pw.z = cvt_pk_bf16(S1[8 * s + 4], S1[8 * s + 5]); pw.w = cvt_pk_bf16(S1[8 * s + 6], S1[8 * s + 7]); }
;                         const u32x2 va = *(const LAS u32x2*)(vb + kt * 8 + 16 * s), vc = *(const LAS u32x2*)(vb + kt * 8 + 16 * s + 8);
;                         const u32x4 vq = (u32x4){va.x, va.y, vc.x, vc.y};
;                         O[e] = __builtin_amdgcn_mfma_f32_32x32x16_bf16(__builtin_bit_cast(bf16x8, vq), __builtin_bit_cast(bf16x8, pw), O[e], 0, 0, 0);
;                     }
	v_max3_f32 v4, v223, v4, v53
	v_sub_f32_e32 v53, v223, v4
	v_exp_f32_e32 v60, v53
	v_sub_f32_e32 v43, v43, v4
	v_exp_f32_e32 v43, v43
	v_sub_f32_e32 v59, v227, v4
	v_exp_f32_e32 v59, v59
	v_sub_f32_e32 v44, v44, v4
	v_exp_f32_e32 v44, v44
	v_sub_f32_e32 v39, v39, v4
	v_pk_mul_f32 v[6:7], v[6:7], v[60:61] op_sel_hi:[1,0]
	v_pk_mul_f32 v[8:9], v[8:9], v[60:61] op_sel_hi:[1,0]
	v_exp_f32_e32 v61, v39
	v_add_f32_e32 v53, 0, v43
	v_add_f32_e32 v53, v59, v53
	v_add_f32_e32 v53, v44, v53
	v_sub_f32_e32 v40, v40, v4
	v_add_f32_e32 v39, v61, v53
	v_exp_f32_e32 v53, v40
	v_sub_f32_e32 v40, v47, v4
	v_exp_f32_e32 v47, v40
	v_sub_f32_e32 v40, v41, v4
	v_exp_f32_e32 v62, v40
	v_sub_f32_e32 v40, v48, v4
	v_exp_f32_e32 v48, v40
	v_sub_f32_e32 v40, v42, v4
	v_exp_f32_e32 v63, v40
	v_sub_f32_e32 v40, v54, v4
	v_exp_f32_e32 v54, v40
	v_sub_f32_e32 v40, v45, v4
	v_exp_f32_e32 v64, v40
	v_sub_f32_e32 v40, v55, v4
	v_exp_f32_e32 v55, v40
	v_sub_f32_e32 v40, v49, v4
	v_exp_f32_e32 v49, v40
	v_sub_f32_e32 v40, v56, v4
	v_sub_f32_e32 v46, v46, v4
	v_exp_f32_e32 v56, v40
	v_sub_f32_e32 v40, v50, v4
	v_exp_f32_e32 v46, v46
	v_exp_f32_e32 v50, v40
	v_sub_f32_e32 v40, v57, v4
	v_exp_f32_e32 v57, v40
	v_sub_f32_e32 v40, v51, v4
	v_exp_f32_e32 v51, v40
	v_sub_f32_e32 v40, v58, v4
	v_exp_f32_e32 v58, v40
	v_sub_f32_e32 v40, v52, v4
	v_add_f32_e32 v39, v46, v39
	v_exp_f32_e32 v52, v40
	v_cvt_pk_bf16_f32 v40, v43, v59
	v_cvt_pk_bf16_f32 v41, v44, v61
	v_add_u32_e32 v44, s91, v130
	v_add_f32_e32 v39, v53, v39
	v_cvt_pk_bf16_f32 v42, v46, v53
	v_add_u32_e32 v53, 0xa000, v44
	v_add_f32_e32 v39, v47, v39
	v_cvt_pk_bf16_f32 v43, v47, v62
	ds_read2_b64 v[44:47], v53 offset1:2
	v_pk_mul_f32 v[10:11], v[10:11], v[60:61] op_sel_hi:[1,0]
	v_pk_mul_f32 v[12:13], v[12:13], v[60:61] op_sel_hi:[1,0]
	v_pk_mul_f32 v[14:15], v[14:15], v[60:61] op_sel_hi:[1,0]
	v_pk_mul_f32 v[16:17], v[16:17], v[60:61] op_sel_hi:[1,0]
	v_pk_mul_f32 v[18:19], v[18:19], v[60:61] op_sel_hi:[1,0]
	v_pk_mul_f32 v[20:21], v[20:21], v[60:61] op_sel_hi:[1,0]
	v_add_f32_e32 v39, v62, v39
	v_add_f32_e32 v39, v48, v39
	s_waitcnt lgkmcnt(0)
	v_mfma_f32_32x32x16_bf16 v[6:21], v[44:47], v[40:43], v[6:21]
	v_cvt_pk_bf16_f32 v40, v48, v63
	v_cvt_pk_bf16_f32 v41, v54, v64
	v_cvt_pk_bf16_f32 v42, v55, v56
	v_cvt_pk_bf16_f32 v43, v57, v58
	ds_read2_b64 v[44:47], v53 offset0:4 offset1:6
	v_add_f32_e32 v39, v63, v39
	v_add_f32_e32 v39, v54, v39
	s_waitcnt lgkmcnt(0)
	v_mfma_f32_32x32x16_bf16 v[6:21], v[44:47], v[40:43], v[6:21]
	v_cvt_pk_bf16_f32 v40, v5, v5
	v_cvt_pk_bf16_f32 v41, v5, v5
	v_cvt_pk_bf16_f32 v42, v49, v50
	v_cvt_pk_bf16_f32 v43, v51, v52
	ds_read2_b64 v[44:47], v53 offset0:6 offset1:8
	v_add_f32_e32 v39, v64, v39
	v_add_f32_e32 v39, v55, v39
	v_add_f32_e32 v39, v49, v39
	s_waitcnt lgkmcnt(0)
	v_mfma_f32_32x32x16_bf16 v[6:21], v[44:47], v[40:43], v[6:21]
	v_add_f32_e32 v39, v56, v39
	v_add_f32_e32 v39, v50, v39
	v_add_f32_e32 v39, v57, v39
	v_add_f32_e32 v39, v51, v39
	v_add_f32_e32 v39, v58, v39
	v_add_f32_e32 v39, v52, v39
	v_fmac_f32_e32 v39, v222, v60
	v_add_u32_e32 v214, 0x60000, v214
	v_add_u32_e32 v215, 0x60000, v215
	v_add_u32_e32 v216, 0x60000, v216
	v_add_u32_e32 v218, 0x60000, v218
	v_add_u32_e32 v219, 0x60000, v219
	v_add_u32_e32 v220, 0x60000, v220
	v_add_u32_e32 v221, 0x60000, v221
	s_cmpk_eq_i32 s65, 0x3e0
	s_cbranch_scc1 .LBB1_437
	v_mov_b32_e32 v223, v4
	v_mov_b32_e32 v4, v225
	v_mov_b32_e32 v222, v39
	v_mov_b32_e32 v224, v38
	s_branch .LBB1_455
